# k18: each workgroup issues an early L2 writeback when it arrives at a grid barrier (the XCD leader's writeback then finds little dirty data)
# baseline (speedup 1.0000x reference)
.LBB0_86:
	s_mov_b64 s[0:1], exec
	v_readlane_b32 s6, v254, 11
	s_lshl_b32 s6, s6, 8
	v_readlane_b32 s8, v254, 12
	v_mbcnt_lo_u32_b32 v1, s0, 0
	v_readlane_b32 s9, v254, 13
	s_add_u32 s6, s8, s6
	v_mbcnt_hi_u32_b32 v1, s1, v1
	s_addc_u32 s7, s9, 0
	v_cmp_eq_u32_e32 vcc, 0, v1
	s_and_saveexec_b64 s[8:9], vcc
	s_cbranch_execz .LBB0_88
	s_bcnt1_i32_b64 s0, s[0:1]
	buffer_wbl2 sc1
	v_mov_b32_e32 v3, 0x1000
	v_mov_b32_e32 v4, s0
	global_atomic_add v3, v3, v4, s[6:7] offset:1024 sc0

.LBB0_218:
	s_mov_b64 s[0:1], exec
	v_readlane_b32 s4, v254, 11
	s_lshl_b32 s4, s4, 8
	v_readlane_b32 s8, v254, 12
	v_mbcnt_lo_u32_b32 v1, s0, 0
	v_readlane_b32 s9, v254, 13
	s_add_u32 s10, s8, s4
	v_mbcnt_hi_u32_b32 v1, s1, v1
	s_addc_u32 s11, s9, 0
	v_cmp_eq_u32_e32 vcc, 0, v1
	s_and_saveexec_b64 s[4:5], vcc
	s_cbranch_execz .LBB0_220
	s_bcnt1_i32_b64 s0, s[0:1]
	buffer_wbl2 sc1
	v_mov_b32_e32 v3, 0x1000
	v_mov_b32_e32 v4, s0
	global_atomic_add v3, v3, v4, s[10:11] offset:1024 sc0

.LBB0_416:
	s_mov_b64 s[0:1], exec
	v_readlane_b32 s4, v254, 11
	s_lshl_b32 s4, s4, 8
	v_readlane_b32 s8, v254, 12
	v_mbcnt_lo_u32_b32 v1, s0, 0
	v_readlane_b32 s9, v254, 13
	s_add_u32 s8, s8, s4
	v_mbcnt_hi_u32_b32 v1, s1, v1
	s_addc_u32 s9, s9, 0
	v_cmp_eq_u32_e32 vcc, 0, v1
	s_and_saveexec_b64 s[4:5], vcc
	s_cbranch_execz .LBB0_418
	s_bcnt1_i32_b64 s0, s[0:1]
	buffer_wbl2 sc1
	v_mov_b32_e32 v3, 0x1000
	v_mov_b32_e32 v4, s0
	global_atomic_add v3, v3, v4, s[8:9] offset:1024 sc0

.LBB0_503:
	s_mov_b64 s[4:5], exec
	v_readlane_b32 s6, v254, 11
	s_lshl_b32 s6, s6, 8
	v_readlane_b32 s8, v254, 12
	v_mbcnt_lo_u32_b32 v1, s4, 0
	v_readlane_b32 s9, v254, 13
	s_add_u32 s6, s8, s6
	v_mbcnt_hi_u32_b32 v1, s5, v1
	s_addc_u32 s7, s9, 0
	v_cmp_eq_u32_e32 vcc, 0, v1
	s_and_saveexec_b64 s[8:9], vcc
	s_cbranch_execz .LBB0_505
	s_bcnt1_i32_b64 s4, s[4:5]
	buffer_wbl2 sc1
	v_mov_b32_e32 v3, 0x1000
	v_mov_b32_e32 v4, s4
	global_atomic_add v3, v3, v4, s[6:7] offset:1024 sc0

.LBB0_866:
	s_mov_b64 s[4:5], exec
	s_lshl_b32 s6, s53, 8
	v_mbcnt_lo_u32_b32 v1, s4, 0
	s_add_u32 s6, s96, s6
	v_mbcnt_hi_u32_b32 v1, s5, v1
	s_addc_u32 s7, s97, 0
	v_cmp_eq_u32_e32 vcc, 0, v1
	s_and_saveexec_b64 s[8:9], vcc
	s_cbranch_execz .LBB0_868
	s_bcnt1_i32_b64 s4, s[4:5]
	buffer_wbl2 sc1
	v_mov_b32_e32 v3, 0x1000
	v_mov_b32_e32 v4, s4
	global_atomic_add v3, v3, v4, s[6:7] offset:1024 sc0

.LBB0_1723:
	s_mov_b64 s[4:5], exec
	s_lshl_b32 s2, s53, 8
	v_mbcnt_lo_u32_b32 v1, s4, 0
	s_add_u32 s2, s96, s2
	v_mbcnt_hi_u32_b32 v1, s5, v1
	s_addc_u32 s3, s97, 0
	v_cmp_eq_u32_e32 vcc, 0, v1
	s_and_saveexec_b64 s[6:7], vcc
	s_cbranch_execz .LBB0_1725
	s_bcnt1_i32_b64 s4, s[4:5]
	buffer_wbl2 sc1
	v_mov_b32_e32 v3, 0x1000
	v_mov_b32_e32 v4, s4
	global_atomic_add v3, v3, v4, s[2:3] offset:1024 sc0
